# speedup vs baseline: 1.0031x; 1.0031x over previous
; #define LAS __attribute__((address_space(3)))
; __device__ __forceinline__ s16x4 vtr(const LAS char* p) { return __builtin_bit_cast(s16x4, __builtin_amdgcn_ds_read_tr16_b64_v4i16((LAS v4i16_t*)p)); }
; template <int DQK>
; __device__ __forceinline__ void attn_unit64(LAS char* lds, const bf16x8 (&qa)[DQK / 16], const bf16x8 (&qb)[DQK / 16],
;                                             const bf16_t* Kg, int ldk, const bf16_t* Vg, int ldv, int t0, int t1, bf16_t* Oga, int ogb_off) {
;     ...
;             for (int ds = 0; ds < DQK / 16; ++ds) {
;                 const bf16x8 kf = *(const LAS bf16x8*)(kb + kv * 32 * KP + ds * 32);
;                 sa = __builtin_amdgcn_mfma_f32_32x32x16_bf16(kf, qa[ds], sa, 0, 0, 0);
;                 sb = __builtin_amdgcn_mfma_f32_32x32x16_bf16(kf, qb[ds], sb, 0, 0, 0);
;             }
; #pragma unroll
;             for (int i = 0; i < 16; i += 2) { sa[i] = __builtin_amdgcn_exp2f(sa[i]); sa[i + 1] = __builtin_amdgcn_exp2f(sa[i + 1]); la0 += sa[i]; la1 += sa[i + 1];
;                                                sb[i] = __builtin_amdgcn_exp2f(sb[i]); sb[i + 1] = __builtin_amdgcn_exp2f(sb[i + 1]); lb0 += sb[i]; lb1 += sb[i + 1]; }
;             bf16x8 pa[2], pb[2]; pa[0] = pack8(sa, 0); pa[1] = pack8(sa, 1); pb[0] = pack8(sb, 0); pb[1] = pack8(sb, 1);
; #pragma unroll
;             for (int s2 = 0; s2 < 2; ++s2) {
;                 const int s = 2 * kv + s2;
;                 const s16x4 a0 = vtr(vb + (16 * s) * 64), a1 = vtr(vb + (16 * s + 8) * 64), c0 = vtr(vb + 4096 + (16 * s) * 64), c1 = vtr(vb + 4096 + (16 * s + 8) * 64);
;                 const bf16x8 va = (bf16x8){a0[0], a0[1], a0[2], a0[3], a1[0], a1[1], a1[2], a1[3]}, vc = (bf16x8){c0[0], c0[1], c0[2], c0[3], c1[0], c1[1], c1[2], c1[3]};
;                 oa0 = __builtin_amdgcn_mfma_f32_32x32x16_bf16(va, pa[s2], oa0, 0, 0, 0);
;                 oa1 = __builtin_amdgcn_mfma_f32_32x32x16_bf16(vc, pa[s2], oa1, 0, 0, 0);
;                 ob0 = __builtin_amdgcn_mfma_f32_32x32x16_bf16(va, pb[s2], ob0, 0, 0, 0);
;                 ob1 = __builtin_amdgcn_mfma_f32_32x32x16_bf16(vc, pb[s2], ob1, 0, 0, 0);
;             }
.Lp11_g1_pro:
	s_mov_b32 s24, 0x2000
	s_mov_b32 s25, 0
	v_lshl_add_u64 v[180:181], v[168:169], 0, s[24:25]
	global_load_dwordx4 v[104:107], v[180:181], off
	v_mov_b32_e32 v240, v238
	v_add_u32_e32 v241, s99, v238
	v_mov_b32_e32 v242, v239
	v_add_u32_e32 v243, s99, v159
	v_add_u32_e32 v244, s99, v212
	v_add_u32_e32 v245, s99, v179
	v_mov_b32_e32 v68, 0xf149f2ca
	v_mov_b32_e32 v69, v68
	v_mov_b32_e32 v70, v68
	v_mov_b32_e32 v71, v68
	v_mov_b32_e32 v72, v68
	v_mov_b32_e32 v73, v68
	v_mov_b32_e32 v74, v68
	v_mov_b32_e32 v75, v68
	v_mov_b32_e32 v76, v68
	v_mov_b32_e32 v77, v68
	v_mov_b32_e32 v78, v68
	v_mov_b32_e32 v79, v68
	v_mov_b32_e32 v64, 0
	v_mov_b32_e32 v65, 0
	v_mov_b32_e32 v66, 0
	v_mov_b32_e32 v67, 0
	v_mov_b32_e32 v230, 0
	v_mov_b32_e32 v231, 0
	v_mov_b32_e32 v214, 0
	v_mov_b32_e32 v215, 0
	v_mov_b32_e32 v216, 0
	v_mov_b32_e32 v217, 0
	v_mov_b32_e32 v218, 0
	v_mov_b32_e32 v219, 0
	v_mov_b32_e32 v220, 0
	v_mov_b32_e32 v221, 0
	v_mov_b32_e32 v248, 0
	v_mov_b32_e32 v249, 0
	v_mov_b32_e32 v250, 0
	v_mov_b32_e32 v251, 0
	v_mov_b32_e32 v252, 0
	v_mov_b32_e32 v253, 0
	v_mov_b32_e32 v254, 0
	v_mov_b32_e32 v255, 0
.Lp11_loop:
	s_waitcnt lgkmcnt(0)
	v_mfma_f32_32x32x16_bf16 v[80:95], v[182:185], v[128:131], 0
	v_exp_f32_e32 v68, v68
	v_exp_f32_e32 v69, v69
	v_add_f32_e32 v172, v172, v64
	v_cvt_pk_bf16_f32 v232, v68, v69
	v_mfma_f32_32x32x16_bf16 v[80:95], v[186:189], v[124:127], v[80:95]
	v_exp_f32_e32 v70, v70
	v_exp_f32_e32 v71, v71
	v_add_f32_e32 v173, v173, v65
	v_cvt_pk_bf16_f32 v233, v70, v71
	v_mfma_f32_32x32x16_bf16 v[80:95], v[190:193], v[120:123], v[80:95]
	v_exp_f32_e32 v72, v72
	v_exp_f32_e32 v73, v73
	v_add_f32_e32 v172, v172, v66
	v_cvt_pk_bf16_f32 v234, v72, v73
	v_mfma_f32_32x32x16_bf16 v[80:95], v[194:197], v[116:119], v[80:95]
	v_exp_f32_e32 v74, v74
	v_exp_f32_e32 v75, v75
	v_add_f32_e32 v173, v173, v67
	v_cvt_pk_bf16_f32 v235, v74, v75
	v_mfma_f32_32x32x16_bf16 v[80:95], v[198:201], v[108:111], v[80:95]
	v_exp_f32_e32 v76, v76
	v_exp_f32_e32 v77, v77
	v_add_f32_e32 v172, v172, v68
	v_cvt_pk_bf16_f32 v236, v76, v77
	v_mfma_f32_32x32x16_bf16 v[80:95], v[202:205], v[112:115], v[80:95]
	v_exp_f32_e32 v78, v78
	v_exp_f32_e32 v79, v79
	v_add_f32_e32 v173, v173, v69
	v_cvt_pk_bf16_f32 v237, v78, v79
	v_mfma_f32_32x32x16_bf16 v[16:31], v[248:251], v[230:233], v[16:31]
	ds_read_b64_tr_b16 v[248:249], v242 offset:13312
	ds_read_b64_tr_b16 v[250:251], v242 offset:13824
	v_add_f32_e32 v172, v172, v70
	v_add_f32_e32 v173, v173, v71
	v_add_f32_e32 v172, v172, v72
	v_add_f32_e32 v173, v173, v73
	v_mfma_f32_32x32x16_bf16 v[0:15], v[252:255], v[230:233], v[0:15]
	ds_read_b64_tr_b16 v[252:253], v242 offset:17408
	ds_read_b64_tr_b16 v[254:255], v242 offset:17920
	v_add_f32_e32 v172, v172, v74
	v_add_f32_e32 v173, v173, v75
	v_exp_f32_e32 v80, v80
	v_exp_f32_e32 v81, v81
	v_mfma_f32_32x32x16_bf16 v[16:31], v[214:217], v[234:237], v[16:31]
	ds_read_b64_tr_b16 v[214:215], v242 offset:14336
	ds_read_b64_tr_b16 v[216:217], v242 offset:14848
	v_add_f32_e32 v172, v172, v76
	v_exp_f32_e32 v82, v82
	v_add_f32_e32 v173, v173, v77
	v_cvt_pk_bf16_f32 v222, v80, v81
	v_mfma_f32_32x32x16_bf16 v[0:15], v[218:221], v[234:237], v[0:15]
	ds_read_b64_tr_b16 v[218:219], v242 offset:18432
	ds_read_b64_tr_b16 v[220:221], v242 offset:18944
	v_exp_f32_e32 v83, v83
	v_add_f32_e32 v172, v172, v78
	v_add_f32_e32 v173, v173, v79
	v_cvt_pk_bf16_f32 v223, v82, v83
	v_mfma_f32_32x32x16_bf16 v[64:79], v[182:185], v[132:135], 0
	ds_read_b128 v[182:185], v240 offset:6656
	v_exp_f32_e32 v84, v84
	v_exp_f32_e32 v85, v85
	v_add_f32_e32 v170, v170, v80
	v_cvt_pk_bf16_f32 v224, v84, v85
	v_mfma_f32_32x32x16_bf16 v[64:79], v[186:189], v[136:139], v[64:79]
	ds_read_b128 v[186:189], v240 offset:6688
	v_exp_f32_e32 v86, v86
	v_exp_f32_e32 v87, v87
	v_add_f32_e32 v171, v171, v81
	v_cvt_pk_bf16_f32 v225, v86, v87
	v_mfma_f32_32x32x16_bf16 v[64:79], v[190:193], v[140:143], v[64:79]
	ds_read_b128 v[190:193], v240 offset:6720
	v_exp_f32_e32 v88, v88
	v_exp_f32_e32 v89, v89
	v_add_f32_e32 v170, v170, v82
	v_cvt_pk_bf16_f32 v226, v88, v89
	v_mfma_f32_32x32x16_bf16 v[64:79], v[194:197], v[144:147], v[64:79]
	ds_read_b128 v[194:197], v240 offset:6752
	v_exp_f32_e32 v90, v90
	v_exp_f32_e32 v91, v91
	v_add_f32_e32 v171, v171, v83
	v_cvt_pk_bf16_f32 v227, v90, v91
	v_mfma_f32_32x32x16_bf16 v[64:79], v[198:201], v[148:151], v[64:79]
	ds_read_b128 v[198:201], v240 offset:6784
	v_exp_f32_e32 v92, v92
	v_exp_f32_e32 v93, v93
	v_add_f32_e32 v170, v170, v84
	v_cvt_pk_bf16_f32 v228, v92, v93
	v_mfma_f32_32x32x16_bf16 v[64:79], v[202:205], v[152:155], v[64:79]
	ds_read_b128 v[202:205], v240 offset:6816
	v_exp_f32_e32 v94, v94
	v_exp_f32_e32 v95, v95
	v_add_f32_e32 v171, v171, v85
	v_cvt_pk_bf16_f32 v229, v94, v95
	s_waitcnt lgkmcnt(6)
	v_mfma_f32_32x32x16_bf16 v[32:47], v[248:251], v[222:225], v[32:47]
	v_add_f32_e32 v170, v170, v86
	v_add_f32_e32 v171, v171, v87
	v_add_f32_e32 v170, v170, v88
	v_add_f32_e32 v171, v171, v89
	s_waitcnt vmcnt(0)
	ds_write_b128 v243, v[96:99]
	s_cmp_eq_u64 s[0:1], 0
	v_mfma_f32_32x32x16_bf16 v[48:63], v[252:255], v[222:225], v[48:63]
	v_add_f32_e32 v170, v170, v90
	v_add_f32_e32 v171, v171, v91
	v_exp_f32_e32 v64, v64
	v_exp_f32_e32 v65, v65
	s_cbranch_scc1 .Lp11_w1_a
	ds_write_b128 v244, v[100:103]
; #define LAS __attribute__((address_space(3)))
; __device__ __forceinline__ s16x4 vtr(const LAS char* p) { return __builtin_bit_cast(s16x4, __builtin_amdgcn_ds_read_tr16_b64_v4i16((LAS v4i16_t*)p)); }
; template <int DQK>
; __device__ __forceinline__ void attn_unit64(LAS char* lds, const bf16x8 (&qa)[DQK / 16], const bf16x8 (&qb)[DQK / 16],
;                                             const bf16_t* Kg, int ldk, const bf16_t* Vg, int ldv, int t0, int t1, bf16_t* Oga, int ogb_off) {
;     ...
;             for (int ds = 0; ds < DQK / 16; ++ds) {
;                 const bf16x8 kf = *(const LAS bf16x8*)(kb + kv * 32 * KP + ds * 32);
;                 sa = __builtin_amdgcn_mfma_f32_32x32x16_bf16(kf, qa[ds], sa, 0, 0, 0);
;                 sb = __builtin_amdgcn_mfma_f32_32x32x16_bf16(kf, qb[ds], sb, 0, 0, 0);
;             }
; #pragma unroll
;             for (int i = 0; i < 16; i += 2) { sa[i] = __builtin_amdgcn_exp2f(sa[i]); sa[i + 1] = __builtin_amdgcn_exp2f(sa[i + 1]); la0 += sa[i]; la1 += sa[i + 1];
;                                                sb[i] = __builtin_amdgcn_exp2f(sb[i]); sb[i + 1] = __builtin_amdgcn_exp2f(sb[i + 1]); lb0 += sb[i]; lb1 += sb[i + 1]; }
;             bf16x8 pa[2], pb[2]; pa[0] = pack8(sa, 0); pa[1] = pack8(sa, 1); pb[0] = pack8(sb, 0); pb[1] = pack8(sb, 1);
; #pragma unroll
;             for (int s2 = 0; s2 < 2; ++s2) {
;                 const int s = 2 * kv + s2;
;                 const s16x4 a0 = vtr(vb + (16 * s) * 64), a1 = vtr(vb + (16 * s + 8) * 64), c0 = vtr(vb + 4096 + (16 * s) * 64), c1 = vtr(vb + 4096 + (16 * s + 8) * 64);
;                 const bf16x8 va = (bf16x8){a0[0], a0[1], a0[2], a0[3], a1[0], a1[1], a1[2], a1[3]}, vc = (bf16x8){c0[0], c0[1], c0[2], c0[3], c1[0], c1[1], c1[2], c1[3]};
;                 oa0 = __builtin_amdgcn_mfma_f32_32x32x16_bf16(va, pa[s2], oa0, 0, 0, 0);
;                 oa1 = __builtin_amdgcn_mfma_f32_32x32x16_bf16(vc, pa[s2], oa1, 0, 0, 0);
;                 ob0 = __builtin_amdgcn_mfma_f32_32x32x16_bf16(va, pb[s2], ob0, 0, 0, 0);
;                 ob1 = __builtin_amdgcn_mfma_f32_32x32x16_bf16(vc, pb[s2], ob1, 0, 0, 0);
;             }
;         }
;         if (more) { const unsigned bo = (cur ^ 1) * BUF; *(LAS u32x4*)(lds + bo + kdst0) = kreg0; if (k2) *(LAS u32x4*)(lds + bo + kdst1) = kreg1; *(LAS u32x4*)(lds + bo + vdst) = vreg; }
;         __syncthreads();
.Lp11_w1_a:
	ds_write_b128 v245, v[104:107] offset:13312
	s_add_i32 s20, s4, 2
	s_min_u32 s20, s20, s101
	v_mfma_f32_32x32x16_bf16 v[32:47], v[214:217], v[226:229], v[32:47]
	v_add_f32_e32 v170, v170, v92
	v_exp_f32_e32 v66, v66
	v_add_f32_e32 v171, v171, v93
	v_cvt_pk_bf16_f32 v230, v64, v65
	s_mul_i32 s22, s20, 0x3000
	s_mul_hi_u32 s23, s20, 0x3000
	s_add_u32 s22, s18, s22
	s_addc_u32 s23, s19, s23
	s_lshl_b32 s24, s20, 13
	s_mov_b32 s25, 0
	v_lshl_add_u64 v[180:181], v[168:169], 0, s[24:25]
	v_mfma_f32_32x32x16_bf16 v[48:63], v[218:221], v[226:229], v[48:63]
	v_exp_f32_e32 v67, v67
	v_add_f32_e32 v170, v170, v94
	v_add_f32_e32 v171, v171, v95
	v_cvt_pk_bf16_f32 v231, v66, v67
	global_load_dwordx4 v[96:99], v160, s[22:23]
	s_cmp_eq_u64 s[0:1], 0
	s_cbranch_scc1 .Lp11_g1_a
	global_load_dwordx4 v[100:103], v166, s[22:23]
.Lp11_g1_a:
	global_load_dwordx4 v[104:107], v[180:181], off
	s_waitcnt lgkmcnt(2)
	v_mfma_f32_32x32x16_bf16 v[80:95], v[182:185], v[128:131], 0
	v_exp_f32_e32 v68, v68
	v_exp_f32_e32 v69, v69
	v_add_f32_e32 v172, v172, v64
	v_cvt_pk_bf16_f32 v232, v68, v69
	v_mfma_f32_32x32x16_bf16 v[80:95], v[186:189], v[124:127], v[80:95]
	v_exp_f32_e32 v70, v70
	v_exp_f32_e32 v71, v71
	v_add_f32_e32 v173, v173, v65
	v_cvt_pk_bf16_f32 v233, v70, v71
	v_mfma_f32_32x32x16_bf16 v[80:95], v[190:193], v[120:123], v[80:95]
	v_exp_f32_e32 v72, v72
	v_exp_f32_e32 v73, v73
	v_add_f32_e32 v172, v172, v66
	v_cvt_pk_bf16_f32 v234, v72, v73
	v_mfma_f32_32x32x16_bf16 v[80:95], v[194:197], v[116:119], v[80:95]
	v_exp_f32_e32 v74, v74
	v_exp_f32_e32 v75, v75
	v_add_f32_e32 v173, v173, v67
	v_cvt_pk_bf16_f32 v235, v74, v75
	v_mfma_f32_32x32x16_bf16 v[80:95], v[198:201], v[108:111], v[80:95]
	v_exp_f32_e32 v76, v76
	v_exp_f32_e32 v77, v77
	v_add_f32_e32 v172, v172, v68
	v_cvt_pk_bf16_f32 v236, v76, v77
	v_mfma_f32_32x32x16_bf16 v[80:95], v[202:205], v[112:115], v[80:95]
	v_exp_f32_e32 v78, v78
	v_exp_f32_e32 v79, v79
	v_add_f32_e32 v173, v173, v69
	v_cvt_pk_bf16_f32 v237, v78, v79
	v_mfma_f32_32x32x16_bf16 v[16:31], v[248:251], v[230:233], v[16:31]
	ds_read_b64_tr_b16 v[248:249], v242 offset:15360
	ds_read_b64_tr_b16 v[250:251], v242 offset:15872
	v_add_f32_e32 v172, v172, v70
	v_add_f32_e32 v173, v173, v71
	v_add_f32_e32 v172, v172, v72
	v_add_f32_e32 v173, v173, v73
	v_mfma_f32_32x32x16_bf16 v[0:15], v[252:255], v[230:233], v[0:15]
	ds_read_b64_tr_b16 v[252:253], v242 offset:19456
	ds_read_b64_tr_b16 v[254:255], v242 offset:19968
	v_add_f32_e32 v172, v172, v74
	v_add_f32_e32 v173, v173, v75
	v_exp_f32_e32 v80, v80
	v_exp_f32_e32 v81, v81
	v_mfma_f32_32x32x16_bf16 v[16:31], v[214:217], v[234:237], v[16:31]
	ds_read_b64_tr_b16 v[214:215], v242 offset:16384
	ds_read_b64_tr_b16 v[216:217], v242 offset:16896
	v_add_f32_e32 v172, v172, v76
	v_exp_f32_e32 v82, v82
	v_add_f32_e32 v173, v173, v77
	v_cvt_pk_bf16_f32 v222, v80, v81
	v_mfma_f32_32x32x16_bf16 v[0:15], v[218:221], v[234:237], v[0:15]
	ds_read_b64_tr_b16 v[218:219], v242 offset:20480
	ds_read_b64_tr_b16 v[220:221], v242 offset:20992
	v_exp_f32_e32 v83, v83
	v_add_f32_e32 v172, v172, v78
	v_add_f32_e32 v173, v173, v79
	v_cvt_pk_bf16_f32 v223, v82, v83
	s_waitcnt lgkmcnt(8)
	s_barrier
	v_mfma_f32_32x32x16_bf16 v[64:79], v[182:185], v[132:135], 0
	ds_read_b128 v[182:185], v241
	v_exp_f32_e32 v84, v84
	v_exp_f32_e32 v85, v85
	v_add_f32_e32 v170, v170, v80
	v_cvt_pk_bf16_f32 v224, v84, v85
	v_mfma_f32_32x32x16_bf16 v[64:79], v[186:189], v[136:139], v[64:79]
	ds_read_b128 v[186:189], v241 offset:32
	v_exp_f32_e32 v86, v86
	v_exp_f32_e32 v87, v87
	v_add_f32_e32 v171, v171, v81
	v_cvt_pk_bf16_f32 v225, v86, v87
	v_mfma_f32_32x32x16_bf16 v[64:79], v[190:193], v[140:143], v[64:79]
	ds_read_b128 v[190:193], v241 offset:64
	v_exp_f32_e32 v88, v88
	v_exp_f32_e32 v89, v89
	v_add_f32_e32 v170, v170, v82
	v_cvt_pk_bf16_f32 v226, v88, v89
	v_mfma_f32_32x32x16_bf16 v[64:79], v[194:197], v[144:147], v[64:79]
	ds_read_b128 v[194:197], v241 offset:96
	v_exp_f32_e32 v90, v90
	v_exp_f32_e32 v91, v91
	v_add_f32_e32 v171, v171, v83
	v_cvt_pk_bf16_f32 v227, v90, v91
	v_mfma_f32_32x32x16_bf16 v[64:79], v[198:201], v[148:151], v[64:79]
	ds_read_b128 v[198:201], v241 offset:128
	v_exp_f32_e32 v92, v92
	v_exp_f32_e32 v93, v93
	v_add_f32_e32 v170, v170, v84
	v_cvt_pk_bf16_f32 v228, v92, v93
	v_mfma_f32_32x32x16_bf16 v[64:79], v[202:205], v[152:155], v[64:79]
	ds_read_b128 v[202:205], v241 offset:160
	v_exp_f32_e32 v94, v94
	v_exp_f32_e32 v95, v95
	v_add_f32_e32 v171, v171, v85
	v_cvt_pk_bf16_f32 v229, v94, v95
	s_waitcnt lgkmcnt(6)
	v_mfma_f32_32x32x16_bf16 v[32:47], v[248:251], v[222:225], v[32:47]
	v_add_f32_e32 v170, v170, v86
	v_add_f32_e32 v171, v171, v87
	v_add_f32_e32 v170, v170, v88
	v_add_f32_e32 v171, v171, v89
	v_mfma_f32_32x32x16_bf16 v[48:63], v[252:255], v[222:225], v[48:63]
	v_add_f32_e32 v170, v170, v90
	v_add_f32_e32 v171, v171, v91
	v_exp_f32_e32 v64, v64
	v_exp_f32_e32 v65, v65
	s_mov_b32 s20, s98
	s_mov_b32 s98, s99
	s_mov_b32 s99, s100
	s_mov_b32 s100, s20
	v_mfma_f32_32x32x16_bf16 v[32:47], v[214:217], v[226:229], v[32:47]
	v_add_f32_e32 v170, v170, v92
	v_exp_f32_e32 v66, v66
	v_add_f32_e32 v171, v171, v93
	v_cvt_pk_bf16_f32 v230, v64, v65
	v_add_u32_e32 v240, s98, v238
	v_add_u32_e32 v241, s99, v238
	v_add_u32_e32 v242, s98, v239
	v_mfma_f32_32x32x16_bf16 v[48:63], v[218:221], v[226:229], v[48:63]
	v_exp_f32_e32 v67, v67
	v_add_f32_e32 v170, v170, v94
	v_add_f32_e32 v171, v171, v95
	v_cvt_pk_bf16_f32 v231, v66, v67
	v_add_u32_e32 v243, s99, v159
	v_add_u32_e32 v244, s99, v212
	v_add_u32_e32 v245, s99, v179
	s_add_i32 s4, s4, 1
	s_cmp_lt_u32 s4, s39
	s_cbranch_scc1 .Lp11_loop
	v_exp_f32_e32 v68, v68
	v_exp_f32_e32 v69, v69
	v_exp_f32_e32 v70, v70
	v_exp_f32_e32 v71, v71
	v_cvt_pk_bf16_f32 v232, v68, v69
	v_exp_f32_e32 v72, v72
	v_exp_f32_e32 v73, v73
	v_cvt_pk_bf16_f32 v233, v70, v71
	v_exp_f32_e32 v74, v74
	v_exp_f32_e32 v75, v75
	v_cvt_pk_bf16_f32 v234, v72, v73
	v_exp_f32_e32 v76, v76
	v_exp_f32_e32 v77, v77
	v_cvt_pk_bf16_f32 v235, v74, v75
	v_exp_f32_e32 v78, v78
	v_exp_f32_e32 v79, v79
	v_cvt_pk_bf16_f32 v236, v76, v77
	v_add_f32_e32 v172, v172, v64
	v_cvt_pk_bf16_f32 v237, v78, v79
	v_add_f32_e32 v173, v173, v65
	v_add_f32_e32 v172, v172, v66
	v_add_f32_e32 v173, v173, v67
	v_add_f32_e32 v172, v172, v68
	v_add_f32_e32 v173, v173, v69
	v_add_f32_e32 v172, v172, v70
	v_add_f32_e32 v173, v173, v71
	v_add_f32_e32 v172, v172, v72
	v_add_f32_e32 v173, v173, v73
	v_add_f32_e32 v172, v172, v74
	v_add_f32_e32 v173, v173, v75
	v_add_f32_e32 v172, v172, v76
	v_add_f32_e32 v173, v173, v77
	v_add_f32_e32 v172, v172, v78
	v_add_f32_e32 v173, v173, v79
	s_nop 1
	v_mfma_f32_32x32x16_bf16 v[16:31], v[248:251], v[230:233], v[16:31]
	v_mfma_f32_32x32x16_bf16 v[0:15], v[252:255], v[230:233], v[0:15]
	v_mfma_f32_32x32x16_bf16 v[16:31], v[214:217], v[234:237], v[16:31]
	v_mfma_f32_32x32x16_bf16 v[0:15], v[218:221], v[234:237], v[0:15]
	s_waitcnt vmcnt(0)
	s_waitcnt lgkmcnt(0)
	s_barrier
	s_branch .LBB0_1115
